# Shared rmsnorm pre-pass rewritten by hand: 4 rows per batch, double-buffered loads (next batch in flight while reducing)
# speedup vs baseline: 1.0080x; 1.0050x over previous
; __device__ __forceinline__ unsigned cvt_pk_bf16(float lo, float hi) { unsigned r; asm volatile("v_cvt_pk_bf16_f32 %0, %1, %2" : "=v"(r) : "v"(lo), "v"(hi)); return r; }
; __device__ __forceinline__ void rows_prenorm(const float* __restrict__ x, bf16_t* __restrict__ XN, float* __restrict__ RN, int bi, int nb, int nrows) {
;     const int lane = threadIdx.x & 63, gw = bi * 8 + (threadIdx.x >> 6), nw = nb * 8;
;     for (int row = gw; row < nrows; row += 2 * nw) {
;         f32x4 v[2][4]; float ss[2] = {0.f, 0.f};
; #pragma unroll
;         for (int u = 0; u < 2; ++u) { const float* xp = x + (size_t)(row + u * nw) * DM + 4 * lane;
; #pragma unroll
;             for (int c = 0; c < 4; ++c) v[u][c] = *(const f32x4*)(xp + 256 * c); }
; #pragma unroll
;         for (int u = 0; u < 2; ++u) {
; #pragma unroll
;             for (int c = 0; c < 4; ++c) ss[u] += sq4(v[u][c]);
;             ss[u] = wave_sum(ss[u]); const float ms = ss[u] * (1.0f / DM) + EPS, ri = rsqrtf(ms);
;             if (lane == 0) RN[row + u * nw] = ms * ri;
;             bf16_t* op = XN + (size_t)(row + u * nw) * DM + 4 * lane;
; #pragma unroll
;             for (int c = 0; c < 4; ++c) { u32x2 w; w.x = cvt_pk_bf16(v[u][c][0] * ri, v[u][c][1] * ri); w.y = cvt_pk_bf16(v[u][c][2] * ri, v[u][c][3] * ri); *(u32x2*)(op + 256 * c) = w; } }
; __global__ void __launch_bounds__(512, 2) mk_fwd(Args a) {
;     ...
;       rows_prenorm(a.in[0], (bf16_t*)(ws + WS_XN), (float*)(ws + WS_RN), bx, G, T); }
.LBB0_29:
	s_or_b64 exec, exec, s[0:1]
	s_add_u32 s0, s90, 0x3800000
	s_addc_u32 s1, s91, 0
	v_writelane_b32 v245, s0, 16
	s_add_u32 s6, s90, 0x1f810000
	s_addc_u32 s7, s91, 0
	v_writelane_b32 v245, s1, 17
	s_mov_b32 s0, 0x8000
	v_cmp_gt_i32_e32 vcc, s0, v176
	v_mbcnt_lo_u32_b32 v188, -1, 0
	v_lshlrev_b32_e32 v152, 3, v165
	s_and_saveexec_b64 s[2:3], vcc
	s_cbranch_execz .LBB0_36
	s_waitcnt vmcnt(0)
	v_mov_b32_e32 v92, v176
	v_mov_b32_e32 v93, 0
	v_lshlrev_b32_e32 v0, 4, v165
	v_mov_b32_e32 v1, 0
	v_lshl_add_u64 v[88:89], s[4:5], 0, v[0:1]
	v_readlane_b32 s0, v245, 16
	v_readlane_b32 s1, v245, 17
	v_lshlrev_b32_e32 v0, 3, v165
	s_nop 1
	v_lshl_add_u64 v[90:91], s[0:1], 0, v[0:1]
	v_mbcnt_hi_u32_b32 v0, -1, v188
	v_xor_b32_e32 v1, 32, v0
	v_lshlrev_b32_e32 v80, 2, v1
	v_xor_b32_e32 v1, 16, v0
	v_lshlrev_b32_e32 v81, 2, v1
	v_xor_b32_e32 v1, 8, v0
	v_lshlrev_b32_e32 v82, 2, v1
	v_xor_b32_e32 v1, 4, v0
	v_lshlrev_b32_e32 v83, 2, v1
	v_xor_b32_e32 v1, 2, v0
	v_lshlrev_b32_e32 v84, 2, v1
	v_xor_b32_e32 v1, 1, v0
	v_lshlrev_b32_e32 v85, 2, v1
	v_mov_b32_e32 v86, 0x358637bd
	v_lshlrev_b64 v[94:95], 12, v[92:93]
	v_lshl_add_u64 v[94:95], v[88:89], 0, v[94:95]
	global_load_dwordx4 v[0:3], v[94:95], off
	global_load_dwordx4 v[4:7], v[94:95], off offset:1024
	global_load_dwordx4 v[8:11], v[94:95], off offset:2048
	global_load_dwordx4 v[12:15], v[94:95], off offset:3072
	v_add_u32_e32 v160, 0x800, v92
	v_mov_b32_e32 v161, 0
	v_lshlrev_b64 v[94:95], 12, v[160:161]
	v_lshl_add_u64 v[94:95], v[88:89], 0, v[94:95]
	global_load_dwordx4 v[16:19], v[94:95], off
	global_load_dwordx4 v[20:23], v[94:95], off offset:1024
	global_load_dwordx4 v[24:27], v[94:95], off offset:2048
	global_load_dwordx4 v[28:31], v[94:95], off offset:3072
	v_add_u32_e32 v160, 0x1000, v92
	v_mov_b32_e32 v161, 0
	v_lshlrev_b64 v[94:95], 12, v[160:161]
	v_lshl_add_u64 v[94:95], v[88:89], 0, v[94:95]
	global_load_dwordx4 v[32:35], v[94:95], off
	global_load_dwordx4 v[36:39], v[94:95], off offset:1024
	global_load_dwordx4 v[40:43], v[94:95], off offset:2048
	global_load_dwordx4 v[44:47], v[94:95], off offset:3072
	v_add_u32_e32 v160, 0x1800, v92
	v_mov_b32_e32 v161, 0
	v_lshlrev_b64 v[94:95], 12, v[160:161]
	v_lshl_add_u64 v[94:95], v[88:89], 0, v[94:95]
	global_load_dwordx4 v[48:51], v[94:95], off
	global_load_dwordx4 v[52:55], v[94:95], off offset:1024
	global_load_dwordx4 v[56:59], v[94:95], off offset:2048
	global_load_dwordx4 v[60:63], v[94:95], off offset:3072
	v_add_u32_e32 v160, 0x2000, v92
	v_mov_b32_e32 v161, 0
	v_lshlrev_b64 v[94:95], 12, v[160:161]
	v_lshl_add_u64 v[94:95], v[88:89], 0, v[94:95]
	global_load_dwordx4 v[96:99], v[94:95], off
	global_load_dwordx4 v[100:103], v[94:95], off offset:1024
	global_load_dwordx4 v[104:107], v[94:95], off offset:2048
	global_load_dwordx4 v[108:111], v[94:95], off offset:3072
	v_add_u32_e32 v160, 0x2800, v92
	v_mov_b32_e32 v161, 0
	v_lshlrev_b64 v[94:95], 12, v[160:161]
	v_lshl_add_u64 v[94:95], v[88:89], 0, v[94:95]
	global_load_dwordx4 v[112:115], v[94:95], off
	global_load_dwordx4 v[116:119], v[94:95], off offset:1024
	global_load_dwordx4 v[120:123], v[94:95], off offset:2048
	global_load_dwordx4 v[124:127], v[94:95], off offset:3072
	v_add_u32_e32 v160, 0x3000, v92
	v_mov_b32_e32 v161, 0
	v_lshlrev_b64 v[94:95], 12, v[160:161]
	v_lshl_add_u64 v[94:95], v[88:89], 0, v[94:95]
	global_load_dwordx4 v[128:131], v[94:95], off
	global_load_dwordx4 v[132:135], v[94:95], off offset:1024
	global_load_dwordx4 v[136:139], v[94:95], off offset:2048
	global_load_dwordx4 v[140:143], v[94:95], off offset:3072
	v_add_u32_e32 v160, 0x3800, v92
	v_mov_b32_e32 v161, 0
	v_lshlrev_b64 v[94:95], 12, v[160:161]
	v_lshl_add_u64 v[94:95], v[88:89], 0, v[94:95]
	global_load_dwordx4 v[144:147], v[94:95], off
	global_load_dwordx4 v[148:151], v[94:95], off offset:1024
	global_load_dwordx4 v[152:155], v[94:95], off offset:2048
	global_load_dwordx4 v[156:159], v[94:95], off offset:3072
	s_waitcnt vmcnt(16)
	v_mul_f32_e32 v64, v1, v1
	v_mul_f32_e32 v65, v5, v5
	v_mul_f32_e32 v66, v9, v9
	v_mul_f32_e32 v67, v13, v13
	v_fmac_f32_e32 v64, v0, v0
	v_fmac_f32_e32 v65, v4, v4
	v_fmac_f32_e32 v66, v8, v8
	v_fmac_f32_e32 v67, v12, v12
	v_fmac_f32_e32 v64, v2, v2
	v_fmac_f32_e32 v65, v6, v6
	v_fmac_f32_e32 v66, v10, v10
	v_fmac_f32_e32 v67, v14, v14
	v_fmac_f32_e32 v64, v3, v3
	v_fmac_f32_e32 v65, v7, v7
	v_fmac_f32_e32 v66, v11, v11
	v_fmac_f32_e32 v67, v15, v15
	v_add_f32_e32 v68, v64, v65
	v_add_f32_e32 v68, v68, v66
	v_add_f32_e32 v68, v68, v67
	ds_bpermute_b32 v69, v80, v68
	s_waitcnt lgkmcnt(0)
	v_add_f32_e32 v68, v68, v69
	ds_bpermute_b32 v69, v81, v68
	s_waitcnt lgkmcnt(0)
	v_add_f32_e32 v68, v68, v69
	ds_bpermute_b32 v69, v82, v68
	s_waitcnt lgkmcnt(0)
	v_add_f32_e32 v68, v68, v69
	ds_bpermute_b32 v69, v83, v68
	s_waitcnt lgkmcnt(0)
	v_add_f32_e32 v68, v68, v69
	ds_bpermute_b32 v69, v84, v68
	s_waitcnt lgkmcnt(0)
	v_add_f32_e32 v68, v68, v69
	ds_bpermute_b32 v69, v85, v68
	s_waitcnt lgkmcnt(0)
; __device__ __forceinline__ unsigned cvt_pk_bf16(float lo, float hi) { unsigned r; asm volatile("v_cvt_pk_bf16_f32 %0, %1, %2" : "=v"(r) : "v"(lo), "v"(hi)); return r; }
; __device__ __forceinline__ void rows_prenorm(const float* __restrict__ x, bf16_t* __restrict__ XN, float* __restrict__ RN, int bi, int nb, int nrows) {
;     ...
;         for (int u = 0; u < 2; ++u) { const float* xp = x + (size_t)(row + u * nw) * DM + 4 * lane;
; #pragma unroll
;             for (int c = 0; c < 4; ++c) v[u][c] = *(const f32x4*)(xp + 256 * c); }
; #pragma unroll
;         for (int u = 0; u < 2; ++u) {
; #pragma unroll
;             for (int c = 0; c < 4; ++c) ss[u] += sq4(v[u][c]);
;             ss[u] = wave_sum(ss[u]); const float ms = ss[u] * (1.0f / DM) + EPS, ri = rsqrtf(ms);
;             if (lane == 0) RN[row + u * nw] = ms * ri;
;             bf16_t* op = XN + (size_t)(row + u * nw) * DM + 4 * lane;
; #pragma unroll
;             for (int c = 0; c < 4; ++c) { u32x2 w; w.x = cvt_pk_bf16(v[u][c][0] * ri, v[u][c][1] * ri); w.y = cvt_pk_bf16(v[u][c][2] * ri, v[u][c][3] * ri); *(u32x2*)(op + 256 * c) = w; } }
	v_add_f32_e32 v68, v68, v69
	v_fmamk_f32 v69, v68, 0x3a800000, v86
	v_mul_f32_e32 v68, 0x4b800000, v69
	v_cmp_gt_f32_e32 vcc, 0x800000, v69
	s_nop 1
	v_cndmask_b32_e32 v68, v69, v68, vcc
	v_rsq_f32_e32 v68, v68
	s_nop 0
	v_mul_f32_e32 v70, 0x45800000, v68
	v_cndmask_b32_e32 v68, v68, v70, vcc
	v_mov_b32_e32 v160, v92
	v_mov_b32_e32 v161, 0
	v_mul_f32_e32 v69, v69, v68
	v_lshl_add_u64 v[162:163], v[160:161], 2, s[6:7]
	s_mov_b64 exec, 1
	global_store_dword v[162:163], v69, off
	s_mov_b64 exec, -1
	v_lshlrev_b64 v[162:163], 11, v[160:161]
	v_lshl_add_u64 v[162:163], v[90:91], 0, v[162:163]
	v_mul_f32_e32 v0, v0, v68
	v_mul_f32_e32 v1, v1, v68
	v_mul_f32_e32 v2, v2, v68
	v_mul_f32_e32 v3, v3, v68
	v_cvt_pk_bf16_f32 v0, v0, v1
	v_cvt_pk_bf16_f32 v1, v2, v3
	global_store_dwordx2 v[162:163], v[0:1], off
	v_mul_f32_e32 v4, v4, v68
	v_mul_f32_e32 v5, v5, v68
	v_mul_f32_e32 v6, v6, v68
	v_mul_f32_e32 v7, v7, v68
	v_cvt_pk_bf16_f32 v4, v4, v5
	v_cvt_pk_bf16_f32 v5, v6, v7
	global_store_dwordx2 v[162:163], v[4:5], off offset:512
	v_mul_f32_e32 v8, v8, v68
	v_mul_f32_e32 v9, v9, v68
	v_mul_f32_e32 v10, v10, v68
	v_mul_f32_e32 v11, v11, v68
	v_cvt_pk_bf16_f32 v8, v8, v9
	v_cvt_pk_bf16_f32 v9, v10, v11
	global_store_dwordx2 v[162:163], v[8:9], off offset:1024
	v_mul_f32_e32 v12, v12, v68
	v_mul_f32_e32 v13, v13, v68
	v_mul_f32_e32 v14, v14, v68
	v_mul_f32_e32 v15, v15, v68
	v_cvt_pk_bf16_f32 v12, v12, v13
	v_cvt_pk_bf16_f32 v13, v14, v15
	global_store_dwordx2 v[162:163], v[12:13], off offset:1536
	v_mul_f32_e32 v64, v17, v17
	v_mul_f32_e32 v65, v21, v21
	v_mul_f32_e32 v66, v25, v25
	v_mul_f32_e32 v67, v29, v29
	v_fmac_f32_e32 v64, v16, v16
	v_fmac_f32_e32 v65, v20, v20
	v_fmac_f32_e32 v66, v24, v24
	v_fmac_f32_e32 v67, v28, v28
	v_fmac_f32_e32 v64, v18, v18
	v_fmac_f32_e32 v65, v22, v22
	v_fmac_f32_e32 v66, v26, v26
	v_fmac_f32_e32 v67, v30, v30
	v_fmac_f32_e32 v64, v19, v19
	v_fmac_f32_e32 v65, v23, v23
	v_fmac_f32_e32 v66, v27, v27
	v_fmac_f32_e32 v67, v31, v31
	v_add_f32_e32 v68, v64, v65
	v_add_f32_e32 v68, v68, v66
	v_add_f32_e32 v68, v68, v67
	ds_bpermute_b32 v69, v80, v68
	s_waitcnt lgkmcnt(0)
	v_add_f32_e32 v68, v68, v69
	ds_bpermute_b32 v69, v81, v68
	s_waitcnt lgkmcnt(0)
	v_add_f32_e32 v68, v68, v69
	ds_bpermute_b32 v69, v82, v68
	s_waitcnt lgkmcnt(0)
	v_add_f32_e32 v68, v68, v69
	ds_bpermute_b32 v69, v83, v68
	s_waitcnt lgkmcnt(0)
	v_add_f32_e32 v68, v68, v69
	ds_bpermute_b32 v69, v84, v68
	s_waitcnt lgkmcnt(0)
	v_add_f32_e32 v68, v68, v69
	ds_bpermute_b32 v69, v85, v68
	s_waitcnt lgkmcnt(0)
	v_add_f32_e32 v68, v68, v69
	v_fmamk_f32 v69, v68, 0x3a800000, v86
	v_mul_f32_e32 v68, 0x4b800000, v69
	v_cmp_gt_f32_e32 vcc, 0x800000, v69
	s_nop 1
	v_cndmask_b32_e32 v68, v69, v68, vcc
	v_rsq_f32_e32 v68, v68
	s_nop 0
	v_mul_f32_e32 v70, 0x45800000, v68
	v_cndmask_b32_e32 v68, v68, v70, vcc
	v_add_u32_e32 v160, 0x800, v92
	v_mov_b32_e32 v161, 0
	v_mul_f32_e32 v69, v69, v68
	v_lshl_add_u64 v[162:163], v[160:161], 2, s[6:7]
	s_mov_b64 exec, 1
	global_store_dword v[162:163], v69, off
	s_mov_b64 exec, -1
	v_lshlrev_b64 v[162:163], 11, v[160:161]
	v_lshl_add_u64 v[162:163], v[90:91], 0, v[162:163]
	v_mul_f32_e32 v16, v16, v68
	v_mul_f32_e32 v17, v17, v68
	v_mul_f32_e32 v18, v18, v68
	v_mul_f32_e32 v19, v19, v68
	v_cvt_pk_bf16_f32 v16, v16, v17
	v_cvt_pk_bf16_f32 v17, v18, v19
	global_store_dwordx2 v[162:163], v[16:17], off
	v_mul_f32_e32 v20, v20, v68
	v_mul_f32_e32 v21, v21, v68
	v_mul_f32_e32 v22, v22, v68
	v_mul_f32_e32 v23, v23, v68
	v_cvt_pk_bf16_f32 v20, v20, v21
	v_cvt_pk_bf16_f32 v21, v22, v23
	global_store_dwordx2 v[162:163], v[20:21], off offset:512
	v_mul_f32_e32 v24, v24, v68
	v_mul_f32_e32 v25, v25, v68
	v_mul_f32_e32 v26, v26, v68
	v_mul_f32_e32 v27, v27, v68
	v_cvt_pk_bf16_f32 v24, v24, v25
	v_cvt_pk_bf16_f32 v25, v26, v27
	global_store_dwordx2 v[162:163], v[24:25], off offset:1024
	v_mul_f32_e32 v28, v28, v68
	v_mul_f32_e32 v29, v29, v68
	v_mul_f32_e32 v30, v30, v68
	v_mul_f32_e32 v31, v31, v68
	v_cvt_pk_bf16_f32 v28, v28, v29
	v_cvt_pk_bf16_f32 v29, v30, v31
	global_store_dwordx2 v[162:163], v[28:29], off offset:1536
	v_mul_f32_e32 v64, v33, v33
	v_mul_f32_e32 v65, v37, v37
	v_mul_f32_e32 v66, v41, v41
	v_mul_f32_e32 v67, v45, v45
	v_fmac_f32_e32 v64, v32, v32
	v_fmac_f32_e32 v65, v36, v36
	v_fmac_f32_e32 v66, v40, v40
	v_fmac_f32_e32 v67, v44, v44
	v_fmac_f32_e32 v64, v34, v34
	v_fmac_f32_e32 v65, v38, v38
	v_fmac_f32_e32 v66, v42, v42
	v_fmac_f32_e32 v67, v46, v46
	v_fmac_f32_e32 v64, v35, v35
	v_fmac_f32_e32 v65, v39, v39
	v_fmac_f32_e32 v66, v43, v43
	v_fmac_f32_e32 v67, v47, v47
	v_add_f32_e32 v68, v64, v65
	v_add_f32_e32 v68, v68, v66
	v_add_f32_e32 v68, v68, v67
	ds_bpermute_b32 v69, v80, v68
	s_waitcnt lgkmcnt(0)
	v_add_f32_e32 v68, v68, v69
	ds_bpermute_b32 v69, v81, v68
	s_waitcnt lgkmcnt(0)
	v_add_f32_e32 v68, v68, v69
	ds_bpermute_b32 v69, v82, v68
	s_waitcnt lgkmcnt(0)
	v_add_f32_e32 v68, v68, v69
	ds_bpermute_b32 v69, v83, v68
	s_waitcnt lgkmcnt(0)
	v_add_f32_e32 v68, v68, v69
	ds_bpermute_b32 v69, v84, v68
	s_waitcnt lgkmcnt(0)
	v_add_f32_e32 v68, v68, v69
	ds_bpermute_b32 v69, v85, v68
	s_waitcnt lgkmcnt(0)
; __device__ __forceinline__ unsigned cvt_pk_bf16(float lo, float hi) { unsigned r; asm volatile("v_cvt_pk_bf16_f32 %0, %1, %2" : "=v"(r) : "v"(lo), "v"(hi)); return r; }
; __device__ __forceinline__ void rows_prenorm(const float* __restrict__ x, bf16_t* __restrict__ XN, float* __restrict__ RN, int bi, int nb, int nrows) {
;     ...
;         for (int u = 0; u < 2; ++u) { const float* xp = x + (size_t)(row + u * nw) * DM + 4 * lane;
; #pragma unroll
;             for (int c = 0; c < 4; ++c) v[u][c] = *(const f32x4*)(xp + 256 * c); }
; #pragma unroll
;         for (int u = 0; u < 2; ++u) {
; #pragma unroll
;             for (int c = 0; c < 4; ++c) ss[u] += sq4(v[u][c]);
;             ss[u] = wave_sum(ss[u]); const float ms = ss[u] * (1.0f / DM) + EPS, ri = rsqrtf(ms);
;             if (lane == 0) RN[row + u * nw] = ms * ri;
;             bf16_t* op = XN + (size_t)(row + u * nw) * DM + 4 * lane;
; #pragma unroll
;             for (int c = 0; c < 4; ++c) { u32x2 w; w.x = cvt_pk_bf16(v[u][c][0] * ri, v[u][c][1] * ri); w.y = cvt_pk_bf16(v[u][c][2] * ri, v[u][c][3] * ri); *(u32x2*)(op + 256 * c) = w; } }
	v_add_f32_e32 v68, v68, v69
	v_fmamk_f32 v69, v68, 0x3a800000, v86
	v_mul_f32_e32 v68, 0x4b800000, v69
	v_cmp_gt_f32_e32 vcc, 0x800000, v69
	s_nop 1
	v_cndmask_b32_e32 v68, v69, v68, vcc
	v_rsq_f32_e32 v68, v68
	s_nop 0
	v_mul_f32_e32 v70, 0x45800000, v68
	v_cndmask_b32_e32 v68, v68, v70, vcc
	v_add_u32_e32 v160, 0x1000, v92
	v_mov_b32_e32 v161, 0
	v_mul_f32_e32 v69, v69, v68
	v_lshl_add_u64 v[162:163], v[160:161], 2, s[6:7]
	s_mov_b64 exec, 1
	global_store_dword v[162:163], v69, off
	s_mov_b64 exec, -1
	v_lshlrev_b64 v[162:163], 11, v[160:161]
	v_lshl_add_u64 v[162:163], v[90:91], 0, v[162:163]
	v_mul_f32_e32 v32, v32, v68
	v_mul_f32_e32 v33, v33, v68
	v_mul_f32_e32 v34, v34, v68
	v_mul_f32_e32 v35, v35, v68
	v_cvt_pk_bf16_f32 v32, v32, v33
	v_cvt_pk_bf16_f32 v33, v34, v35
	global_store_dwordx2 v[162:163], v[32:33], off
	v_mul_f32_e32 v36, v36, v68
	v_mul_f32_e32 v37, v37, v68
	v_mul_f32_e32 v38, v38, v68
	v_mul_f32_e32 v39, v39, v68
	v_cvt_pk_bf16_f32 v36, v36, v37
	v_cvt_pk_bf16_f32 v37, v38, v39
	global_store_dwordx2 v[162:163], v[36:37], off offset:512
	v_mul_f32_e32 v40, v40, v68
	v_mul_f32_e32 v41, v41, v68
	v_mul_f32_e32 v42, v42, v68
	v_mul_f32_e32 v43, v43, v68
	v_cvt_pk_bf16_f32 v40, v40, v41
	v_cvt_pk_bf16_f32 v41, v42, v43
	global_store_dwordx2 v[162:163], v[40:41], off offset:1024
	v_mul_f32_e32 v44, v44, v68
	v_mul_f32_e32 v45, v45, v68
	v_mul_f32_e32 v46, v46, v68
	v_mul_f32_e32 v47, v47, v68
	v_cvt_pk_bf16_f32 v44, v44, v45
	v_cvt_pk_bf16_f32 v45, v46, v47
	global_store_dwordx2 v[162:163], v[44:45], off offset:1536
	v_mul_f32_e32 v64, v49, v49
	v_mul_f32_e32 v65, v53, v53
	v_mul_f32_e32 v66, v57, v57
	v_mul_f32_e32 v67, v61, v61
	v_fmac_f32_e32 v64, v48, v48
	v_fmac_f32_e32 v65, v52, v52
	v_fmac_f32_e32 v66, v56, v56
	v_fmac_f32_e32 v67, v60, v60
	v_fmac_f32_e32 v64, v50, v50
	v_fmac_f32_e32 v65, v54, v54
	v_fmac_f32_e32 v66, v58, v58
	v_fmac_f32_e32 v67, v62, v62
	v_fmac_f32_e32 v64, v51, v51
	v_fmac_f32_e32 v65, v55, v55
	v_fmac_f32_e32 v66, v59, v59
	v_fmac_f32_e32 v67, v63, v63
	v_add_f32_e32 v68, v64, v65
	v_add_f32_e32 v68, v68, v66
	v_add_f32_e32 v68, v68, v67
	ds_bpermute_b32 v69, v80, v68
	s_waitcnt lgkmcnt(0)
	v_add_f32_e32 v68, v68, v69
	ds_bpermute_b32 v69, v81, v68
	s_waitcnt lgkmcnt(0)
	v_add_f32_e32 v68, v68, v69
	ds_bpermute_b32 v69, v82, v68
	s_waitcnt lgkmcnt(0)
	v_add_f32_e32 v68, v68, v69
	ds_bpermute_b32 v69, v83, v68
	s_waitcnt lgkmcnt(0)
	v_add_f32_e32 v68, v68, v69
	ds_bpermute_b32 v69, v84, v68
	s_waitcnt lgkmcnt(0)
	v_add_f32_e32 v68, v68, v69
	ds_bpermute_b32 v69, v85, v68
	s_waitcnt lgkmcnt(0)
	v_add_f32_e32 v68, v68, v69
	v_fmamk_f32 v69, v68, 0x3a800000, v86
	v_mul_f32_e32 v68, 0x4b800000, v69
	v_cmp_gt_f32_e32 vcc, 0x800000, v69
	s_nop 1
	v_cndmask_b32_e32 v68, v69, v68, vcc
	v_rsq_f32_e32 v68, v68
	s_nop 0
	v_mul_f32_e32 v70, 0x45800000, v68
	v_cndmask_b32_e32 v68, v68, v70, vcc
	v_add_u32_e32 v160, 0x1800, v92
	v_mov_b32_e32 v161, 0
	v_mul_f32_e32 v69, v69, v68
	v_lshl_add_u64 v[162:163], v[160:161], 2, s[6:7]
	s_mov_b64 exec, 1
	global_store_dword v[162:163], v69, off
	s_mov_b64 exec, -1
	v_lshlrev_b64 v[162:163], 11, v[160:161]
	v_lshl_add_u64 v[162:163], v[90:91], 0, v[162:163]
	v_mul_f32_e32 v48, v48, v68
	v_mul_f32_e32 v49, v49, v68
	v_mul_f32_e32 v50, v50, v68
	v_mul_f32_e32 v51, v51, v68
	v_cvt_pk_bf16_f32 v48, v48, v49
	v_cvt_pk_bf16_f32 v49, v50, v51
	global_store_dwordx2 v[162:163], v[48:49], off
	v_mul_f32_e32 v52, v52, v68
	v_mul_f32_e32 v53, v53, v68
	v_mul_f32_e32 v54, v54, v68
	v_mul_f32_e32 v55, v55, v68
	v_cvt_pk_bf16_f32 v52, v52, v53
	v_cvt_pk_bf16_f32 v53, v54, v55
	global_store_dwordx2 v[162:163], v[52:53], off offset:512
	v_mul_f32_e32 v56, v56, v68
	v_mul_f32_e32 v57, v57, v68
	v_mul_f32_e32 v58, v58, v68
	v_mul_f32_e32 v59, v59, v68
	v_cvt_pk_bf16_f32 v56, v56, v57
	v_cvt_pk_bf16_f32 v57, v58, v59
	global_store_dwordx2 v[162:163], v[56:57], off offset:1024
	v_mul_f32_e32 v60, v60, v68
	v_mul_f32_e32 v61, v61, v68
	v_mul_f32_e32 v62, v62, v68
	v_mul_f32_e32 v63, v63, v68
	v_cvt_pk_bf16_f32 v60, v60, v61
	v_cvt_pk_bf16_f32 v61, v62, v63
	global_store_dwordx2 v[162:163], v[60:61], off offset:1536
	v_add_u32_e32 v160, 0x4000, v92
	v_mov_b32_e32 v161, 0
	v_lshlrev_b64 v[94:95], 12, v[160:161]
	v_lshl_add_u64 v[94:95], v[88:89], 0, v[94:95]
	global_load_dwordx4 v[0:3], v[94:95], off
	global_load_dwordx4 v[4:7], v[94:95], off offset:1024
	global_load_dwordx4 v[8:11], v[94:95], off offset:2048
	global_load_dwordx4 v[12:15], v[94:95], off offset:3072
	v_add_u32_e32 v160, 0x4800, v92
	v_mov_b32_e32 v161, 0
	v_lshlrev_b64 v[94:95], 12, v[160:161]
	v_lshl_add_u64 v[94:95], v[88:89], 0, v[94:95]
	global_load_dwordx4 v[16:19], v[94:95], off
	global_load_dwordx4 v[20:23], v[94:95], off offset:1024
	global_load_dwordx4 v[24:27], v[94:95], off offset:2048
	global_load_dwordx4 v[28:31], v[94:95], off offset:3072
	v_add_u32_e32 v160, 0x5000, v92
	v_mov_b32_e32 v161, 0
	v_lshlrev_b64 v[94:95], 12, v[160:161]
	v_lshl_add_u64 v[94:95], v[88:89], 0, v[94:95]
	global_load_dwordx4 v[32:35], v[94:95], off
	global_load_dwordx4 v[36:39], v[94:95], off offset:1024
	global_load_dwordx4 v[40:43], v[94:95], off offset:2048
	global_load_dwordx4 v[44:47], v[94:95], off offset:3072
	v_add_u32_e32 v160, 0x5800, v92
	v_mov_b32_e32 v161, 0
	v_lshlrev_b64 v[94:95], 12, v[160:161]
	v_lshl_add_u64 v[94:95], v[88:89], 0, v[94:95]
	global_load_dwordx4 v[48:51], v[94:95], off
	global_load_dwordx4 v[52:55], v[94:95], off offset:1024
	global_load_dwordx4 v[56:59], v[94:95], off offset:2048
	global_load_dwordx4 v[60:63], v[94:95], off offset:3072
	s_waitcnt vmcnt(36)
; __device__ __forceinline__ unsigned cvt_pk_bf16(float lo, float hi) { unsigned r; asm volatile("v_cvt_pk_bf16_f32 %0, %1, %2" : "=v"(r) : "v"(lo), "v"(hi)); return r; }
; __device__ __forceinline__ void rows_prenorm(const float* __restrict__ x, bf16_t* __restrict__ XN, float* __restrict__ RN, int bi, int nb, int nrows) {
;     ...
;         for (int u = 0; u < 2; ++u) { const float* xp = x + (size_t)(row + u * nw) * DM + 4 * lane;
; #pragma unroll
;             for (int c = 0; c < 4; ++c) v[u][c] = *(const f32x4*)(xp + 256 * c); }
; #pragma unroll
;         for (int u = 0; u < 2; ++u) {
; #pragma unroll
;             for (int c = 0; c < 4; ++c) ss[u] += sq4(v[u][c]);
;             ss[u] = wave_sum(ss[u]); const float ms = ss[u] * (1.0f / DM) + EPS, ri = rsqrtf(ms);
;             if (lane == 0) RN[row + u * nw] = ms * ri;
;             bf16_t* op = XN + (size_t)(row + u * nw) * DM + 4 * lane;
; #pragma unroll
;             for (int c = 0; c < 4; ++c) { u32x2 w; w.x = cvt_pk_bf16(v[u][c][0] * ri, v[u][c][1] * ri); w.y = cvt_pk_bf16(v[u][c][2] * ri, v[u][c][3] * ri); *(u32x2*)(op + 256 * c) = w; } }
	v_mul_f32_e32 v64, v97, v97
	v_mul_f32_e32 v65, v101, v101
	v_mul_f32_e32 v66, v105, v105
	v_mul_f32_e32 v67, v109, v109
	v_fmac_f32_e32 v64, v96, v96
	v_fmac_f32_e32 v65, v100, v100
	v_fmac_f32_e32 v66, v104, v104
	v_fmac_f32_e32 v67, v108, v108
	v_fmac_f32_e32 v64, v98, v98
	v_fmac_f32_e32 v65, v102, v102
	v_fmac_f32_e32 v66, v106, v106
	v_fmac_f32_e32 v67, v110, v110
	v_fmac_f32_e32 v64, v99, v99
	v_fmac_f32_e32 v65, v103, v103
	v_fmac_f32_e32 v66, v107, v107
	v_fmac_f32_e32 v67, v111, v111
	v_add_f32_e32 v68, v64, v65
	v_add_f32_e32 v68, v68, v66
	v_add_f32_e32 v68, v68, v67
	ds_bpermute_b32 v69, v80, v68
	s_waitcnt lgkmcnt(0)
	v_add_f32_e32 v68, v68, v69
	ds_bpermute_b32 v69, v81, v68
	s_waitcnt lgkmcnt(0)
	v_add_f32_e32 v68, v68, v69
	ds_bpermute_b32 v69, v82, v68
	s_waitcnt lgkmcnt(0)
	v_add_f32_e32 v68, v68, v69
	ds_bpermute_b32 v69, v83, v68
	s_waitcnt lgkmcnt(0)
	v_add_f32_e32 v68, v68, v69
	ds_bpermute_b32 v69, v84, v68
	s_waitcnt lgkmcnt(0)
	v_add_f32_e32 v68, v68, v69
	ds_bpermute_b32 v69, v85, v68
	s_waitcnt lgkmcnt(0)
	v_add_f32_e32 v68, v68, v69
	v_fmamk_f32 v69, v68, 0x3a800000, v86
	v_mul_f32_e32 v68, 0x4b800000, v69
	v_cmp_gt_f32_e32 vcc, 0x800000, v69
	s_nop 1
	v_cndmask_b32_e32 v68, v69, v68, vcc
	v_rsq_f32_e32 v68, v68
	s_nop 0
	v_mul_f32_e32 v70, 0x45800000, v68
	v_cndmask_b32_e32 v68, v68, v70, vcc
	v_add_u32_e32 v160, 0x2000, v92
	v_mov_b32_e32 v161, 0
	v_mul_f32_e32 v69, v69, v68
	v_lshl_add_u64 v[162:163], v[160:161], 2, s[6:7]
	s_mov_b64 exec, 1
	global_store_dword v[162:163], v69, off
	s_mov_b64 exec, -1
	v_lshlrev_b64 v[162:163], 11, v[160:161]
	v_lshl_add_u64 v[162:163], v[90:91], 0, v[162:163]
	v_mul_f32_e32 v96, v96, v68
	v_mul_f32_e32 v97, v97, v68
	v_mul_f32_e32 v98, v98, v68
	v_mul_f32_e32 v99, v99, v68
	v_cvt_pk_bf16_f32 v96, v96, v97
	v_cvt_pk_bf16_f32 v97, v98, v99
	global_store_dwordx2 v[162:163], v[96:97], off
	v_mul_f32_e32 v100, v100, v68
	v_mul_f32_e32 v101, v101, v68
	v_mul_f32_e32 v102, v102, v68
	v_mul_f32_e32 v103, v103, v68
	v_cvt_pk_bf16_f32 v100, v100, v101
	v_cvt_pk_bf16_f32 v101, v102, v103
	global_store_dwordx2 v[162:163], v[100:101], off offset:512
	v_mul_f32_e32 v104, v104, v68
	v_mul_f32_e32 v105, v105, v68
	v_mul_f32_e32 v106, v106, v68
	v_mul_f32_e32 v107, v107, v68
	v_cvt_pk_bf16_f32 v104, v104, v105
	v_cvt_pk_bf16_f32 v105, v106, v107
	global_store_dwordx2 v[162:163], v[104:105], off offset:1024
	v_mul_f32_e32 v108, v108, v68
	v_mul_f32_e32 v109, v109, v68
	v_mul_f32_e32 v110, v110, v68
	v_mul_f32_e32 v111, v111, v68
	v_cvt_pk_bf16_f32 v108, v108, v109
	v_cvt_pk_bf16_f32 v109, v110, v111
	global_store_dwordx2 v[162:163], v[108:109], off offset:1536
	v_mul_f32_e32 v64, v113, v113
	v_mul_f32_e32 v65, v117, v117
	v_mul_f32_e32 v66, v121, v121
	v_mul_f32_e32 v67, v125, v125
	v_fmac_f32_e32 v64, v112, v112
	v_fmac_f32_e32 v65, v116, v116
	v_fmac_f32_e32 v66, v120, v120
	v_fmac_f32_e32 v67, v124, v124
	v_fmac_f32_e32 v64, v114, v114
	v_fmac_f32_e32 v65, v118, v118
	v_fmac_f32_e32 v66, v122, v122
	v_fmac_f32_e32 v67, v126, v126
	v_fmac_f32_e32 v64, v115, v115
	v_fmac_f32_e32 v65, v119, v119
	v_fmac_f32_e32 v66, v123, v123
	v_fmac_f32_e32 v67, v127, v127
	v_add_f32_e32 v68, v64, v65
	v_add_f32_e32 v68, v68, v66
	v_add_f32_e32 v68, v68, v67
	ds_bpermute_b32 v69, v80, v68
	s_waitcnt lgkmcnt(0)
	v_add_f32_e32 v68, v68, v69
	ds_bpermute_b32 v69, v81, v68
	s_waitcnt lgkmcnt(0)
	v_add_f32_e32 v68, v68, v69
	ds_bpermute_b32 v69, v82, v68
	s_waitcnt lgkmcnt(0)
	v_add_f32_e32 v68, v68, v69
	ds_bpermute_b32 v69, v83, v68
	s_waitcnt lgkmcnt(0)
	v_add_f32_e32 v68, v68, v69
	ds_bpermute_b32 v69, v84, v68
	s_waitcnt lgkmcnt(0)
	v_add_f32_e32 v68, v68, v69
	ds_bpermute_b32 v69, v85, v68
	s_waitcnt lgkmcnt(0)
	v_add_f32_e32 v68, v68, v69
	v_fmamk_f32 v69, v68, 0x3a800000, v86
	v_mul_f32_e32 v68, 0x4b800000, v69
	v_cmp_gt_f32_e32 vcc, 0x800000, v69
	s_nop 1
	v_cndmask_b32_e32 v68, v69, v68, vcc
	v_rsq_f32_e32 v68, v68
	s_nop 0
	v_mul_f32_e32 v70, 0x45800000, v68
	v_cndmask_b32_e32 v68, v68, v70, vcc
	v_add_u32_e32 v160, 0x2800, v92
	v_mov_b32_e32 v161, 0
	v_mul_f32_e32 v69, v69, v68
	v_lshl_add_u64 v[162:163], v[160:161], 2, s[6:7]
	s_mov_b64 exec, 1
	global_store_dword v[162:163], v69, off
	s_mov_b64 exec, -1
	v_lshlrev_b64 v[162:163], 11, v[160:161]
	v_lshl_add_u64 v[162:163], v[90:91], 0, v[162:163]
	v_mul_f32_e32 v112, v112, v68
	v_mul_f32_e32 v113, v113, v68
	v_mul_f32_e32 v114, v114, v68
	v_mul_f32_e32 v115, v115, v68
	v_cvt_pk_bf16_f32 v112, v112, v113
	v_cvt_pk_bf16_f32 v113, v114, v115
	global_store_dwordx2 v[162:163], v[112:113], off
	v_mul_f32_e32 v116, v116, v68
	v_mul_f32_e32 v117, v117, v68
	v_mul_f32_e32 v118, v118, v68
	v_mul_f32_e32 v119, v119, v68
	v_cvt_pk_bf16_f32 v116, v116, v117
	v_cvt_pk_bf16_f32 v117, v118, v119
	global_store_dwordx2 v[162:163], v[116:117], off offset:512
	v_mul_f32_e32 v120, v120, v68
	v_mul_f32_e32 v121, v121, v68
	v_mul_f32_e32 v122, v122, v68
	v_mul_f32_e32 v123, v123, v68
	v_cvt_pk_bf16_f32 v120, v120, v121
	v_cvt_pk_bf16_f32 v121, v122, v123
	global_store_dwordx2 v[162:163], v[120:121], off offset:1024
	v_mul_f32_e32 v124, v124, v68
	v_mul_f32_e32 v125, v125, v68
	v_mul_f32_e32 v126, v126, v68
	v_mul_f32_e32 v127, v127, v68
	v_cvt_pk_bf16_f32 v124, v124, v125
	v_cvt_pk_bf16_f32 v125, v126, v127
	global_store_dwordx2 v[162:163], v[124:125], off offset:1536
	v_mul_f32_e32 v64, v129, v129
	v_mul_f32_e32 v65, v133, v133
	v_mul_f32_e32 v66, v137, v137
	v_mul_f32_e32 v67, v141, v141
	v_fmac_f32_e32 v64, v128, v128
	v_fmac_f32_e32 v65, v132, v132
	v_fmac_f32_e32 v66, v136, v136
	v_fmac_f32_e32 v67, v140, v140
	v_fmac_f32_e32 v64, v130, v130
	v_fmac_f32_e32 v65, v134, v134
	v_fmac_f32_e32 v66, v138, v138
	v_fmac_f32_e32 v67, v142, v142
	v_fmac_f32_e32 v64, v131, v131
	v_fmac_f32_e32 v65, v135, v135
	v_fmac_f32_e32 v66, v139, v139
	v_fmac_f32_e32 v67, v143, v143
	v_add_f32_e32 v68, v64, v65
	v_add_f32_e32 v68, v68, v66
	v_add_f32_e32 v68, v68, v67
	ds_bpermute_b32 v69, v80, v68
	s_waitcnt lgkmcnt(0)
; __device__ __forceinline__ unsigned cvt_pk_bf16(float lo, float hi) { unsigned r; asm volatile("v_cvt_pk_bf16_f32 %0, %1, %2" : "=v"(r) : "v"(lo), "v"(hi)); return r; }
; __device__ __forceinline__ void rows_prenorm(const float* __restrict__ x, bf16_t* __restrict__ XN, float* __restrict__ RN, int bi, int nb, int nrows) {
;     ...
;         for (int u = 0; u < 2; ++u) { const float* xp = x + (size_t)(row + u * nw) * DM + 4 * lane;
; #pragma unroll
;             for (int c = 0; c < 4; ++c) v[u][c] = *(const f32x4*)(xp + 256 * c); }
; #pragma unroll
;         for (int u = 0; u < 2; ++u) {
; #pragma unroll
;             for (int c = 0; c < 4; ++c) ss[u] += sq4(v[u][c]);
;             ss[u] = wave_sum(ss[u]); const float ms = ss[u] * (1.0f / DM) + EPS, ri = rsqrtf(ms);
;             if (lane == 0) RN[row + u * nw] = ms * ri;
;             bf16_t* op = XN + (size_t)(row + u * nw) * DM + 4 * lane;
; #pragma unroll
;             for (int c = 0; c < 4; ++c) { u32x2 w; w.x = cvt_pk_bf16(v[u][c][0] * ri, v[u][c][1] * ri); w.y = cvt_pk_bf16(v[u][c][2] * ri, v[u][c][3] * ri); *(u32x2*)(op + 256 * c) = w; } }
	v_add_f32_e32 v68, v68, v69
	ds_bpermute_b32 v69, v81, v68
	s_waitcnt lgkmcnt(0)
	v_add_f32_e32 v68, v68, v69
	ds_bpermute_b32 v69, v82, v68
	s_waitcnt lgkmcnt(0)
	v_add_f32_e32 v68, v68, v69
	ds_bpermute_b32 v69, v83, v68
	s_waitcnt lgkmcnt(0)
	v_add_f32_e32 v68, v68, v69
	ds_bpermute_b32 v69, v84, v68
	s_waitcnt lgkmcnt(0)
	v_add_f32_e32 v68, v68, v69
	ds_bpermute_b32 v69, v85, v68
	s_waitcnt lgkmcnt(0)
	v_add_f32_e32 v68, v68, v69
	v_fmamk_f32 v69, v68, 0x3a800000, v86
	v_mul_f32_e32 v68, 0x4b800000, v69
	v_cmp_gt_f32_e32 vcc, 0x800000, v69
	s_nop 1
	v_cndmask_b32_e32 v68, v69, v68, vcc
	v_rsq_f32_e32 v68, v68
	s_nop 0
	v_mul_f32_e32 v70, 0x45800000, v68
	v_cndmask_b32_e32 v68, v68, v70, vcc
	v_add_u32_e32 v160, 0x3000, v92
	v_mov_b32_e32 v161, 0
	v_mul_f32_e32 v69, v69, v68
	v_lshl_add_u64 v[162:163], v[160:161], 2, s[6:7]
	s_mov_b64 exec, 1
	global_store_dword v[162:163], v69, off
	s_mov_b64 exec, -1
	v_lshlrev_b64 v[162:163], 11, v[160:161]
	v_lshl_add_u64 v[162:163], v[90:91], 0, v[162:163]
	v_mul_f32_e32 v128, v128, v68
	v_mul_f32_e32 v129, v129, v68
	v_mul_f32_e32 v130, v130, v68
	v_mul_f32_e32 v131, v131, v68
	v_cvt_pk_bf16_f32 v128, v128, v129
	v_cvt_pk_bf16_f32 v129, v130, v131
	global_store_dwordx2 v[162:163], v[128:129], off
	v_mul_f32_e32 v132, v132, v68
	v_mul_f32_e32 v133, v133, v68
	v_mul_f32_e32 v134, v134, v68
	v_mul_f32_e32 v135, v135, v68
	v_cvt_pk_bf16_f32 v132, v132, v133
	v_cvt_pk_bf16_f32 v133, v134, v135
	global_store_dwordx2 v[162:163], v[132:133], off offset:512
	v_mul_f32_e32 v136, v136, v68
	v_mul_f32_e32 v137, v137, v68
	v_mul_f32_e32 v138, v138, v68
	v_mul_f32_e32 v139, v139, v68
	v_cvt_pk_bf16_f32 v136, v136, v137
	v_cvt_pk_bf16_f32 v137, v138, v139
	global_store_dwordx2 v[162:163], v[136:137], off offset:1024
	v_mul_f32_e32 v140, v140, v68
	v_mul_f32_e32 v141, v141, v68
	v_mul_f32_e32 v142, v142, v68
	v_mul_f32_e32 v143, v143, v68
	v_cvt_pk_bf16_f32 v140, v140, v141
	v_cvt_pk_bf16_f32 v141, v142, v143
	global_store_dwordx2 v[162:163], v[140:141], off offset:1536
	v_mul_f32_e32 v64, v145, v145
	v_mul_f32_e32 v65, v149, v149
	v_mul_f32_e32 v66, v153, v153
	v_mul_f32_e32 v67, v157, v157
	v_fmac_f32_e32 v64, v144, v144
	v_fmac_f32_e32 v65, v148, v148
	v_fmac_f32_e32 v66, v152, v152
	v_fmac_f32_e32 v67, v156, v156
	v_fmac_f32_e32 v64, v146, v146
	v_fmac_f32_e32 v65, v150, v150
	v_fmac_f32_e32 v66, v154, v154
	v_fmac_f32_e32 v67, v158, v158
	v_fmac_f32_e32 v64, v147, v147
	v_fmac_f32_e32 v65, v151, v151
	v_fmac_f32_e32 v66, v155, v155
	v_fmac_f32_e32 v67, v159, v159
	v_add_f32_e32 v68, v64, v65
	v_add_f32_e32 v68, v68, v66
	v_add_f32_e32 v68, v68, v67
	ds_bpermute_b32 v69, v80, v68
	s_waitcnt lgkmcnt(0)
	v_add_f32_e32 v68, v68, v69
	ds_bpermute_b32 v69, v81, v68
	s_waitcnt lgkmcnt(0)
	v_add_f32_e32 v68, v68, v69
	ds_bpermute_b32 v69, v82, v68
	s_waitcnt lgkmcnt(0)
	v_add_f32_e32 v68, v68, v69
	ds_bpermute_b32 v69, v83, v68
	s_waitcnt lgkmcnt(0)
	v_add_f32_e32 v68, v68, v69
	ds_bpermute_b32 v69, v84, v68
	s_waitcnt lgkmcnt(0)
	v_add_f32_e32 v68, v68, v69
	ds_bpermute_b32 v69, v85, v68
	s_waitcnt lgkmcnt(0)
	v_add_f32_e32 v68, v68, v69
	v_fmamk_f32 v69, v68, 0x3a800000, v86
	v_mul_f32_e32 v68, 0x4b800000, v69
	v_cmp_gt_f32_e32 vcc, 0x800000, v69
	s_nop 1
	v_cndmask_b32_e32 v68, v69, v68, vcc
	v_rsq_f32_e32 v68, v68
	s_nop 0
	v_mul_f32_e32 v70, 0x45800000, v68
	v_cndmask_b32_e32 v68, v68, v70, vcc
	v_add_u32_e32 v160, 0x3800, v92
	v_mov_b32_e32 v161, 0
	v_mul_f32_e32 v69, v69, v68
	v_lshl_add_u64 v[162:163], v[160:161], 2, s[6:7]
	s_mov_b64 exec, 1
	global_store_dword v[162:163], v69, off
	s_mov_b64 exec, -1
	v_lshlrev_b64 v[162:163], 11, v[160:161]
	v_lshl_add_u64 v[162:163], v[90:91], 0, v[162:163]
	v_mul_f32_e32 v144, v144, v68
	v_mul_f32_e32 v145, v145, v68
	v_mul_f32_e32 v146, v146, v68
	v_mul_f32_e32 v147, v147, v68
	v_cvt_pk_bf16_f32 v144, v144, v145
	v_cvt_pk_bf16_f32 v145, v146, v147
	global_store_dwordx2 v[162:163], v[144:145], off
	v_mul_f32_e32 v148, v148, v68
	v_mul_f32_e32 v149, v149, v68
	v_mul_f32_e32 v150, v150, v68
	v_mul_f32_e32 v151, v151, v68
	v_cvt_pk_bf16_f32 v148, v148, v149
	v_cvt_pk_bf16_f32 v149, v150, v151
	global_store_dwordx2 v[162:163], v[148:149], off offset:512
	v_mul_f32_e32 v152, v152, v68
	v_mul_f32_e32 v153, v153, v68
	v_mul_f32_e32 v154, v154, v68
	v_mul_f32_e32 v155, v155, v68
	v_cvt_pk_bf16_f32 v152, v152, v153
	v_cvt_pk_bf16_f32 v153, v154, v155
	global_store_dwordx2 v[162:163], v[152:153], off offset:1024
	v_mul_f32_e32 v156, v156, v68
	v_mul_f32_e32 v157, v157, v68
	v_mul_f32_e32 v158, v158, v68
	v_mul_f32_e32 v159, v159, v68
	v_cvt_pk_bf16_f32 v156, v156, v157
	v_cvt_pk_bf16_f32 v157, v158, v159
	global_store_dwordx2 v[162:163], v[156:157], off offset:1536
	v_add_u32_e32 v160, 0x6000, v92
	v_mov_b32_e32 v161, 0
	v_lshlrev_b64 v[94:95], 12, v[160:161]
	v_lshl_add_u64 v[94:95], v[88:89], 0, v[94:95]
	global_load_dwordx4 v[96:99], v[94:95], off
	global_load_dwordx4 v[100:103], v[94:95], off offset:1024
	global_load_dwordx4 v[104:107], v[94:95], off offset:2048
	global_load_dwordx4 v[108:111], v[94:95], off offset:3072
	v_add_u32_e32 v160, 0x6800, v92
	v_mov_b32_e32 v161, 0
	v_lshlrev_b64 v[94:95], 12, v[160:161]
	v_lshl_add_u64 v[94:95], v[88:89], 0, v[94:95]
	global_load_dwordx4 v[112:115], v[94:95], off
	global_load_dwordx4 v[116:119], v[94:95], off offset:1024
	global_load_dwordx4 v[120:123], v[94:95], off offset:2048
	global_load_dwordx4 v[124:127], v[94:95], off offset:3072
	v_add_u32_e32 v160, 0x7000, v92
	v_mov_b32_e32 v161, 0
	v_lshlrev_b64 v[94:95], 12, v[160:161]
	v_lshl_add_u64 v[94:95], v[88:89], 0, v[94:95]
	global_load_dwordx4 v[128:131], v[94:95], off
	global_load_dwordx4 v[132:135], v[94:95], off offset:1024
	global_load_dwordx4 v[136:139], v[94:95], off offset:2048
	global_load_dwordx4 v[140:143], v[94:95], off offset:3072
	v_add_u32_e32 v160, 0x7800, v92
	v_mov_b32_e32 v161, 0
	v_lshlrev_b64 v[94:95], 12, v[160:161]
	v_lshl_add_u64 v[94:95], v[88:89], 0, v[94:95]
	global_load_dwordx4 v[144:147], v[94:95], off
	global_load_dwordx4 v[148:151], v[94:95], off offset:1024
	global_load_dwordx4 v[152:155], v[94:95], off offset:2048
	global_load_dwordx4 v[156:159], v[94:95], off offset:3072
	s_waitcnt vmcnt(36)
; __device__ __forceinline__ unsigned cvt_pk_bf16(float lo, float hi) { unsigned r; asm volatile("v_cvt_pk_bf16_f32 %0, %1, %2" : "=v"(r) : "v"(lo), "v"(hi)); return r; }
; __device__ __forceinline__ void rows_prenorm(const float* __restrict__ x, bf16_t* __restrict__ XN, float* __restrict__ RN, int bi, int nb, int nrows) {
;     ...
;         for (int u = 0; u < 2; ++u) { const float* xp = x + (size_t)(row + u * nw) * DM + 4 * lane;
; #pragma unroll
;             for (int c = 0; c < 4; ++c) v[u][c] = *(const f32x4*)(xp + 256 * c); }
; #pragma unroll
;         for (int u = 0; u < 2; ++u) {
; #pragma unroll
;             for (int c = 0; c < 4; ++c) ss[u] += sq4(v[u][c]);
;             ss[u] = wave_sum(ss[u]); const float ms = ss[u] * (1.0f / DM) + EPS, ri = rsqrtf(ms);
;             if (lane == 0) RN[row + u * nw] = ms * ri;
;             bf16_t* op = XN + (size_t)(row + u * nw) * DM + 4 * lane;
; #pragma unroll
;             for (int c = 0; c < 4; ++c) { u32x2 w; w.x = cvt_pk_bf16(v[u][c][0] * ri, v[u][c][1] * ri); w.y = cvt_pk_bf16(v[u][c][2] * ri, v[u][c][3] * ri); *(u32x2*)(op + 256 * c) = w; } }
	v_mul_f32_e32 v64, v1, v1
	v_mul_f32_e32 v65, v5, v5
	v_mul_f32_e32 v66, v9, v9
	v_mul_f32_e32 v67, v13, v13
	v_fmac_f32_e32 v64, v0, v0
	v_fmac_f32_e32 v65, v4, v4
	v_fmac_f32_e32 v66, v8, v8
	v_fmac_f32_e32 v67, v12, v12
	v_fmac_f32_e32 v64, v2, v2
	v_fmac_f32_e32 v65, v6, v6
	v_fmac_f32_e32 v66, v10, v10
	v_fmac_f32_e32 v67, v14, v14
	v_fmac_f32_e32 v64, v3, v3
	v_fmac_f32_e32 v65, v7, v7
	v_fmac_f32_e32 v66, v11, v11
	v_fmac_f32_e32 v67, v15, v15
	v_add_f32_e32 v68, v64, v65
	v_add_f32_e32 v68, v68, v66
	v_add_f32_e32 v68, v68, v67
	ds_bpermute_b32 v69, v80, v68
	s_waitcnt lgkmcnt(0)
	v_add_f32_e32 v68, v68, v69
	ds_bpermute_b32 v69, v81, v68
	s_waitcnt lgkmcnt(0)
	v_add_f32_e32 v68, v68, v69
	ds_bpermute_b32 v69, v82, v68
	s_waitcnt lgkmcnt(0)
	v_add_f32_e32 v68, v68, v69
	ds_bpermute_b32 v69, v83, v68
	s_waitcnt lgkmcnt(0)
	v_add_f32_e32 v68, v68, v69
	ds_bpermute_b32 v69, v84, v68
	s_waitcnt lgkmcnt(0)
	v_add_f32_e32 v68, v68, v69
	ds_bpermute_b32 v69, v85, v68
	s_waitcnt lgkmcnt(0)
	v_add_f32_e32 v68, v68, v69
	v_fmamk_f32 v69, v68, 0x3a800000, v86
	v_mul_f32_e32 v68, 0x4b800000, v69
	v_cmp_gt_f32_e32 vcc, 0x800000, v69
	s_nop 1
	v_cndmask_b32_e32 v68, v69, v68, vcc
	v_rsq_f32_e32 v68, v68
	s_nop 0
	v_mul_f32_e32 v70, 0x45800000, v68
	v_cndmask_b32_e32 v68, v68, v70, vcc
	v_add_u32_e32 v160, 0x4000, v92
	v_mov_b32_e32 v161, 0
	v_mul_f32_e32 v69, v69, v68
	v_lshl_add_u64 v[162:163], v[160:161], 2, s[6:7]
	s_mov_b64 exec, 1
	global_store_dword v[162:163], v69, off
	s_mov_b64 exec, -1
	v_lshlrev_b64 v[162:163], 11, v[160:161]
	v_lshl_add_u64 v[162:163], v[90:91], 0, v[162:163]
	v_mul_f32_e32 v0, v0, v68
	v_mul_f32_e32 v1, v1, v68
	v_mul_f32_e32 v2, v2, v68
	v_mul_f32_e32 v3, v3, v68
	v_cvt_pk_bf16_f32 v0, v0, v1
	v_cvt_pk_bf16_f32 v1, v2, v3
	global_store_dwordx2 v[162:163], v[0:1], off
	v_mul_f32_e32 v4, v4, v68
	v_mul_f32_e32 v5, v5, v68
	v_mul_f32_e32 v6, v6, v68
	v_mul_f32_e32 v7, v7, v68
	v_cvt_pk_bf16_f32 v4, v4, v5
	v_cvt_pk_bf16_f32 v5, v6, v7
	global_store_dwordx2 v[162:163], v[4:5], off offset:512
	v_mul_f32_e32 v8, v8, v68
	v_mul_f32_e32 v9, v9, v68
	v_mul_f32_e32 v10, v10, v68
	v_mul_f32_e32 v11, v11, v68
	v_cvt_pk_bf16_f32 v8, v8, v9
	v_cvt_pk_bf16_f32 v9, v10, v11
	global_store_dwordx2 v[162:163], v[8:9], off offset:1024
	v_mul_f32_e32 v12, v12, v68
	v_mul_f32_e32 v13, v13, v68
	v_mul_f32_e32 v14, v14, v68
	v_mul_f32_e32 v15, v15, v68
	v_cvt_pk_bf16_f32 v12, v12, v13
	v_cvt_pk_bf16_f32 v13, v14, v15
	global_store_dwordx2 v[162:163], v[12:13], off offset:1536
	v_mul_f32_e32 v64, v17, v17
	v_mul_f32_e32 v65, v21, v21
	v_mul_f32_e32 v66, v25, v25
	v_mul_f32_e32 v67, v29, v29
	v_fmac_f32_e32 v64, v16, v16
	v_fmac_f32_e32 v65, v20, v20
	v_fmac_f32_e32 v66, v24, v24
	v_fmac_f32_e32 v67, v28, v28
	v_fmac_f32_e32 v64, v18, v18
	v_fmac_f32_e32 v65, v22, v22
	v_fmac_f32_e32 v66, v26, v26
	v_fmac_f32_e32 v67, v30, v30
	v_fmac_f32_e32 v64, v19, v19
	v_fmac_f32_e32 v65, v23, v23
	v_fmac_f32_e32 v66, v27, v27
	v_fmac_f32_e32 v67, v31, v31
	v_add_f32_e32 v68, v64, v65
	v_add_f32_e32 v68, v68, v66
	v_add_f32_e32 v68, v68, v67
	ds_bpermute_b32 v69, v80, v68
	s_waitcnt lgkmcnt(0)
	v_add_f32_e32 v68, v68, v69
	ds_bpermute_b32 v69, v81, v68
	s_waitcnt lgkmcnt(0)
	v_add_f32_e32 v68, v68, v69
	ds_bpermute_b32 v69, v82, v68
	s_waitcnt lgkmcnt(0)
	v_add_f32_e32 v68, v68, v69
	ds_bpermute_b32 v69, v83, v68
	s_waitcnt lgkmcnt(0)
	v_add_f32_e32 v68, v68, v69
	ds_bpermute_b32 v69, v84, v68
	s_waitcnt lgkmcnt(0)
	v_add_f32_e32 v68, v68, v69
	ds_bpermute_b32 v69, v85, v68
	s_waitcnt lgkmcnt(0)
	v_add_f32_e32 v68, v68, v69
	v_fmamk_f32 v69, v68, 0x3a800000, v86
	v_mul_f32_e32 v68, 0x4b800000, v69
	v_cmp_gt_f32_e32 vcc, 0x800000, v69
	s_nop 1
	v_cndmask_b32_e32 v68, v69, v68, vcc
	v_rsq_f32_e32 v68, v68
	s_nop 0
	v_mul_f32_e32 v70, 0x45800000, v68
	v_cndmask_b32_e32 v68, v68, v70, vcc
	v_add_u32_e32 v160, 0x4800, v92
	v_mov_b32_e32 v161, 0
	v_mul_f32_e32 v69, v69, v68
	v_lshl_add_u64 v[162:163], v[160:161], 2, s[6:7]
	s_mov_b64 exec, 1
	global_store_dword v[162:163], v69, off
	s_mov_b64 exec, -1
	v_lshlrev_b64 v[162:163], 11, v[160:161]
	v_lshl_add_u64 v[162:163], v[90:91], 0, v[162:163]
	v_mul_f32_e32 v16, v16, v68
	v_mul_f32_e32 v17, v17, v68
	v_mul_f32_e32 v18, v18, v68
	v_mul_f32_e32 v19, v19, v68
	v_cvt_pk_bf16_f32 v16, v16, v17
	v_cvt_pk_bf16_f32 v17, v18, v19
	global_store_dwordx2 v[162:163], v[16:17], off
	v_mul_f32_e32 v20, v20, v68
	v_mul_f32_e32 v21, v21, v68
	v_mul_f32_e32 v22, v22, v68
	v_mul_f32_e32 v23, v23, v68
	v_cvt_pk_bf16_f32 v20, v20, v21
	v_cvt_pk_bf16_f32 v21, v22, v23
	global_store_dwordx2 v[162:163], v[20:21], off offset:512
	v_mul_f32_e32 v24, v24, v68
	v_mul_f32_e32 v25, v25, v68
	v_mul_f32_e32 v26, v26, v68
	v_mul_f32_e32 v27, v27, v68
	v_cvt_pk_bf16_f32 v24, v24, v25
	v_cvt_pk_bf16_f32 v25, v26, v27
	global_store_dwordx2 v[162:163], v[24:25], off offset:1024
	v_mul_f32_e32 v28, v28, v68
	v_mul_f32_e32 v29, v29, v68
	v_mul_f32_e32 v30, v30, v68
	v_mul_f32_e32 v31, v31, v68
	v_cvt_pk_bf16_f32 v28, v28, v29
	v_cvt_pk_bf16_f32 v29, v30, v31
	global_store_dwordx2 v[162:163], v[28:29], off offset:1536
	v_mul_f32_e32 v64, v33, v33
	v_mul_f32_e32 v65, v37, v37
	v_mul_f32_e32 v66, v41, v41
	v_mul_f32_e32 v67, v45, v45
	v_fmac_f32_e32 v64, v32, v32
	v_fmac_f32_e32 v65, v36, v36
	v_fmac_f32_e32 v66, v40, v40
	v_fmac_f32_e32 v67, v44, v44
	v_fmac_f32_e32 v64, v34, v34
	v_fmac_f32_e32 v65, v38, v38
	v_fmac_f32_e32 v66, v42, v42
	v_fmac_f32_e32 v67, v46, v46
	v_fmac_f32_e32 v64, v35, v35
	v_fmac_f32_e32 v65, v39, v39
	v_fmac_f32_e32 v66, v43, v43
	v_fmac_f32_e32 v67, v47, v47
	v_add_f32_e32 v68, v64, v65
	v_add_f32_e32 v68, v68, v66
	v_add_f32_e32 v68, v68, v67
	ds_bpermute_b32 v69, v80, v68
	s_waitcnt lgkmcnt(0)
; __device__ __forceinline__ unsigned cvt_pk_bf16(float lo, float hi) { unsigned r; asm volatile("v_cvt_pk_bf16_f32 %0, %1, %2" : "=v"(r) : "v"(lo), "v"(hi)); return r; }
; __device__ __forceinline__ void rows_prenorm(const float* __restrict__ x, bf16_t* __restrict__ XN, float* __restrict__ RN, int bi, int nb, int nrows) {
;     ...
;         for (int u = 0; u < 2; ++u) { const float* xp = x + (size_t)(row + u * nw) * DM + 4 * lane;
; #pragma unroll
;             for (int c = 0; c < 4; ++c) v[u][c] = *(const f32x4*)(xp + 256 * c); }
; #pragma unroll
;         for (int u = 0; u < 2; ++u) {
; #pragma unroll
;             for (int c = 0; c < 4; ++c) ss[u] += sq4(v[u][c]);
;             ss[u] = wave_sum(ss[u]); const float ms = ss[u] * (1.0f / DM) + EPS, ri = rsqrtf(ms);
;             if (lane == 0) RN[row + u * nw] = ms * ri;
;             bf16_t* op = XN + (size_t)(row + u * nw) * DM + 4 * lane;
; #pragma unroll
;             for (int c = 0; c < 4; ++c) { u32x2 w; w.x = cvt_pk_bf16(v[u][c][0] * ri, v[u][c][1] * ri); w.y = cvt_pk_bf16(v[u][c][2] * ri, v[u][c][3] * ri); *(u32x2*)(op + 256 * c) = w; } }
	v_add_f32_e32 v68, v68, v69
	ds_bpermute_b32 v69, v81, v68
	s_waitcnt lgkmcnt(0)
	v_add_f32_e32 v68, v68, v69
	ds_bpermute_b32 v69, v82, v68
	s_waitcnt lgkmcnt(0)
	v_add_f32_e32 v68, v68, v69
	ds_bpermute_b32 v69, v83, v68
	s_waitcnt lgkmcnt(0)
	v_add_f32_e32 v68, v68, v69
	ds_bpermute_b32 v69, v84, v68
	s_waitcnt lgkmcnt(0)
	v_add_f32_e32 v68, v68, v69
	ds_bpermute_b32 v69, v85, v68
	s_waitcnt lgkmcnt(0)
	v_add_f32_e32 v68, v68, v69
	v_fmamk_f32 v69, v68, 0x3a800000, v86
	v_mul_f32_e32 v68, 0x4b800000, v69
	v_cmp_gt_f32_e32 vcc, 0x800000, v69
	s_nop 1
	v_cndmask_b32_e32 v68, v69, v68, vcc
	v_rsq_f32_e32 v68, v68
	s_nop 0
	v_mul_f32_e32 v70, 0x45800000, v68
	v_cndmask_b32_e32 v68, v68, v70, vcc
	v_add_u32_e32 v160, 0x5000, v92
	v_mov_b32_e32 v161, 0
	v_mul_f32_e32 v69, v69, v68
	v_lshl_add_u64 v[162:163], v[160:161], 2, s[6:7]
	s_mov_b64 exec, 1
	global_store_dword v[162:163], v69, off
	s_mov_b64 exec, -1
	v_lshlrev_b64 v[162:163], 11, v[160:161]
	v_lshl_add_u64 v[162:163], v[90:91], 0, v[162:163]
	v_mul_f32_e32 v32, v32, v68
	v_mul_f32_e32 v33, v33, v68
	v_mul_f32_e32 v34, v34, v68
	v_mul_f32_e32 v35, v35, v68
	v_cvt_pk_bf16_f32 v32, v32, v33
	v_cvt_pk_bf16_f32 v33, v34, v35
	global_store_dwordx2 v[162:163], v[32:33], off
	v_mul_f32_e32 v36, v36, v68
	v_mul_f32_e32 v37, v37, v68
	v_mul_f32_e32 v38, v38, v68
	v_mul_f32_e32 v39, v39, v68
	v_cvt_pk_bf16_f32 v36, v36, v37
	v_cvt_pk_bf16_f32 v37, v38, v39
	global_store_dwordx2 v[162:163], v[36:37], off offset:512
	v_mul_f32_e32 v40, v40, v68
	v_mul_f32_e32 v41, v41, v68
	v_mul_f32_e32 v42, v42, v68
	v_mul_f32_e32 v43, v43, v68
	v_cvt_pk_bf16_f32 v40, v40, v41
	v_cvt_pk_bf16_f32 v41, v42, v43
	global_store_dwordx2 v[162:163], v[40:41], off offset:1024
	v_mul_f32_e32 v44, v44, v68
	v_mul_f32_e32 v45, v45, v68
	v_mul_f32_e32 v46, v46, v68
	v_mul_f32_e32 v47, v47, v68
	v_cvt_pk_bf16_f32 v44, v44, v45
	v_cvt_pk_bf16_f32 v45, v46, v47
	global_store_dwordx2 v[162:163], v[44:45], off offset:1536
	v_mul_f32_e32 v64, v49, v49
	v_mul_f32_e32 v65, v53, v53
	v_mul_f32_e32 v66, v57, v57
	v_mul_f32_e32 v67, v61, v61
	v_fmac_f32_e32 v64, v48, v48
	v_fmac_f32_e32 v65, v52, v52
	v_fmac_f32_e32 v66, v56, v56
	v_fmac_f32_e32 v67, v60, v60
	v_fmac_f32_e32 v64, v50, v50
	v_fmac_f32_e32 v65, v54, v54
	v_fmac_f32_e32 v66, v58, v58
	v_fmac_f32_e32 v67, v62, v62
	v_fmac_f32_e32 v64, v51, v51
	v_fmac_f32_e32 v65, v55, v55
	v_fmac_f32_e32 v66, v59, v59
	v_fmac_f32_e32 v67, v63, v63
	v_add_f32_e32 v68, v64, v65
	v_add_f32_e32 v68, v68, v66
	v_add_f32_e32 v68, v68, v67
	ds_bpermute_b32 v69, v80, v68
	s_waitcnt lgkmcnt(0)
	v_add_f32_e32 v68, v68, v69
	ds_bpermute_b32 v69, v81, v68
	s_waitcnt lgkmcnt(0)
	v_add_f32_e32 v68, v68, v69
	ds_bpermute_b32 v69, v82, v68
	s_waitcnt lgkmcnt(0)
	v_add_f32_e32 v68, v68, v69
	ds_bpermute_b32 v69, v83, v68
	s_waitcnt lgkmcnt(0)
	v_add_f32_e32 v68, v68, v69
	ds_bpermute_b32 v69, v84, v68
	s_waitcnt lgkmcnt(0)
	v_add_f32_e32 v68, v68, v69
	ds_bpermute_b32 v69, v85, v68
	s_waitcnt lgkmcnt(0)
	v_add_f32_e32 v68, v68, v69
	v_fmamk_f32 v69, v68, 0x3a800000, v86
	v_mul_f32_e32 v68, 0x4b800000, v69
	v_cmp_gt_f32_e32 vcc, 0x800000, v69
	s_nop 1
	v_cndmask_b32_e32 v68, v69, v68, vcc
	v_rsq_f32_e32 v68, v68
	s_nop 0
	v_mul_f32_e32 v70, 0x45800000, v68
	v_cndmask_b32_e32 v68, v68, v70, vcc
	v_add_u32_e32 v160, 0x5800, v92
	v_mov_b32_e32 v161, 0
	v_mul_f32_e32 v69, v69, v68
	v_lshl_add_u64 v[162:163], v[160:161], 2, s[6:7]
	s_mov_b64 exec, 1
	global_store_dword v[162:163], v69, off
	s_mov_b64 exec, -1
	v_lshlrev_b64 v[162:163], 11, v[160:161]
	v_lshl_add_u64 v[162:163], v[90:91], 0, v[162:163]
	v_mul_f32_e32 v48, v48, v68
	v_mul_f32_e32 v49, v49, v68
	v_mul_f32_e32 v50, v50, v68
	v_mul_f32_e32 v51, v51, v68
	v_cvt_pk_bf16_f32 v48, v48, v49
	v_cvt_pk_bf16_f32 v49, v50, v51
	global_store_dwordx2 v[162:163], v[48:49], off
	v_mul_f32_e32 v52, v52, v68
	v_mul_f32_e32 v53, v53, v68
	v_mul_f32_e32 v54, v54, v68
	v_mul_f32_e32 v55, v55, v68
	v_cvt_pk_bf16_f32 v52, v52, v53
	v_cvt_pk_bf16_f32 v53, v54, v55
	global_store_dwordx2 v[162:163], v[52:53], off offset:512
	v_mul_f32_e32 v56, v56, v68
	v_mul_f32_e32 v57, v57, v68
	v_mul_f32_e32 v58, v58, v68
	v_mul_f32_e32 v59, v59, v68
	v_cvt_pk_bf16_f32 v56, v56, v57
	v_cvt_pk_bf16_f32 v57, v58, v59
	global_store_dwordx2 v[162:163], v[56:57], off offset:1024
	v_mul_f32_e32 v60, v60, v68
	v_mul_f32_e32 v61, v61, v68
	v_mul_f32_e32 v62, v62, v68
	v_mul_f32_e32 v63, v63, v68
	v_cvt_pk_bf16_f32 v60, v60, v61
	v_cvt_pk_bf16_f32 v61, v62, v63
	global_store_dwordx2 v[162:163], v[60:61], off offset:1536
	s_waitcnt vmcnt(20)
	v_mul_f32_e32 v64, v97, v97
	v_mul_f32_e32 v65, v101, v101
	v_mul_f32_e32 v66, v105, v105
	v_mul_f32_e32 v67, v109, v109
	v_fmac_f32_e32 v64, v96, v96
	v_fmac_f32_e32 v65, v100, v100
	v_fmac_f32_e32 v66, v104, v104
	v_fmac_f32_e32 v67, v108, v108
	v_fmac_f32_e32 v64, v98, v98
	v_fmac_f32_e32 v65, v102, v102
	v_fmac_f32_e32 v66, v106, v106
	v_fmac_f32_e32 v67, v110, v110
	v_fmac_f32_e32 v64, v99, v99
	v_fmac_f32_e32 v65, v103, v103
	v_fmac_f32_e32 v66, v107, v107
	v_fmac_f32_e32 v67, v111, v111
	v_add_f32_e32 v68, v64, v65
	v_add_f32_e32 v68, v68, v66
	v_add_f32_e32 v68, v68, v67
	ds_bpermute_b32 v69, v80, v68
	s_waitcnt lgkmcnt(0)
	v_add_f32_e32 v68, v68, v69
	ds_bpermute_b32 v69, v81, v68
	s_waitcnt lgkmcnt(0)
	v_add_f32_e32 v68, v68, v69
	ds_bpermute_b32 v69, v82, v68
	s_waitcnt lgkmcnt(0)
	v_add_f32_e32 v68, v68, v69
	ds_bpermute_b32 v69, v83, v68
	s_waitcnt lgkmcnt(0)
	v_add_f32_e32 v68, v68, v69
	ds_bpermute_b32 v69, v84, v68
	s_waitcnt lgkmcnt(0)
	v_add_f32_e32 v68, v68, v69
	ds_bpermute_b32 v69, v85, v68
	s_waitcnt lgkmcnt(0)
; __device__ __forceinline__ unsigned cvt_pk_bf16(float lo, float hi) { unsigned r; asm volatile("v_cvt_pk_bf16_f32 %0, %1, %2" : "=v"(r) : "v"(lo), "v"(hi)); return r; }
; __device__ __forceinline__ void rows_prenorm(const float* __restrict__ x, bf16_t* __restrict__ XN, float* __restrict__ RN, int bi, int nb, int nrows) {
;     ...
;         for (int u = 0; u < 2; ++u) { const float* xp = x + (size_t)(row + u * nw) * DM + 4 * lane;
; #pragma unroll
;             for (int c = 0; c < 4; ++c) v[u][c] = *(const f32x4*)(xp + 256 * c); }
; #pragma unroll
;         for (int u = 0; u < 2; ++u) {
; #pragma unroll
;             for (int c = 0; c < 4; ++c) ss[u] += sq4(v[u][c]);
;             ss[u] = wave_sum(ss[u]); const float ms = ss[u] * (1.0f / DM) + EPS, ri = rsqrtf(ms);
;             if (lane == 0) RN[row + u * nw] = ms * ri;
;             bf16_t* op = XN + (size_t)(row + u * nw) * DM + 4 * lane;
; #pragma unroll
;             for (int c = 0; c < 4; ++c) { u32x2 w; w.x = cvt_pk_bf16(v[u][c][0] * ri, v[u][c][1] * ri); w.y = cvt_pk_bf16(v[u][c][2] * ri, v[u][c][3] * ri); *(u32x2*)(op + 256 * c) = w; } }
	v_add_f32_e32 v68, v68, v69
	v_fmamk_f32 v69, v68, 0x3a800000, v86
	v_mul_f32_e32 v68, 0x4b800000, v69
	v_cmp_gt_f32_e32 vcc, 0x800000, v69
	s_nop 1
	v_cndmask_b32_e32 v68, v69, v68, vcc
	v_rsq_f32_e32 v68, v68
	s_nop 0
	v_mul_f32_e32 v70, 0x45800000, v68
	v_cndmask_b32_e32 v68, v68, v70, vcc
	v_add_u32_e32 v160, 0x6000, v92
	v_mov_b32_e32 v161, 0
	v_mul_f32_e32 v69, v69, v68
	v_lshl_add_u64 v[162:163], v[160:161], 2, s[6:7]
	s_mov_b64 exec, 1
	global_store_dword v[162:163], v69, off
	s_mov_b64 exec, -1
	v_lshlrev_b64 v[162:163], 11, v[160:161]
	v_lshl_add_u64 v[162:163], v[90:91], 0, v[162:163]
	v_mul_f32_e32 v96, v96, v68
	v_mul_f32_e32 v97, v97, v68
	v_mul_f32_e32 v98, v98, v68
	v_mul_f32_e32 v99, v99, v68
	v_cvt_pk_bf16_f32 v96, v96, v97
	v_cvt_pk_bf16_f32 v97, v98, v99
	global_store_dwordx2 v[162:163], v[96:97], off
	v_mul_f32_e32 v100, v100, v68
	v_mul_f32_e32 v101, v101, v68
	v_mul_f32_e32 v102, v102, v68
	v_mul_f32_e32 v103, v103, v68
	v_cvt_pk_bf16_f32 v100, v100, v101
	v_cvt_pk_bf16_f32 v101, v102, v103
	global_store_dwordx2 v[162:163], v[100:101], off offset:512
	v_mul_f32_e32 v104, v104, v68
	v_mul_f32_e32 v105, v105, v68
	v_mul_f32_e32 v106, v106, v68
	v_mul_f32_e32 v107, v107, v68
	v_cvt_pk_bf16_f32 v104, v104, v105
	v_cvt_pk_bf16_f32 v105, v106, v107
	global_store_dwordx2 v[162:163], v[104:105], off offset:1024
	v_mul_f32_e32 v108, v108, v68
	v_mul_f32_e32 v109, v109, v68
	v_mul_f32_e32 v110, v110, v68
	v_mul_f32_e32 v111, v111, v68
	v_cvt_pk_bf16_f32 v108, v108, v109
	v_cvt_pk_bf16_f32 v109, v110, v111
	global_store_dwordx2 v[162:163], v[108:109], off offset:1536
	v_mul_f32_e32 v64, v113, v113
	v_mul_f32_e32 v65, v117, v117
	v_mul_f32_e32 v66, v121, v121
	v_mul_f32_e32 v67, v125, v125
	v_fmac_f32_e32 v64, v112, v112
	v_fmac_f32_e32 v65, v116, v116
	v_fmac_f32_e32 v66, v120, v120
	v_fmac_f32_e32 v67, v124, v124
	v_fmac_f32_e32 v64, v114, v114
	v_fmac_f32_e32 v65, v118, v118
	v_fmac_f32_e32 v66, v122, v122
	v_fmac_f32_e32 v67, v126, v126
	v_fmac_f32_e32 v64, v115, v115
	v_fmac_f32_e32 v65, v119, v119
	v_fmac_f32_e32 v66, v123, v123
	v_fmac_f32_e32 v67, v127, v127
	v_add_f32_e32 v68, v64, v65
	v_add_f32_e32 v68, v68, v66
	v_add_f32_e32 v68, v68, v67
	ds_bpermute_b32 v69, v80, v68
	s_waitcnt lgkmcnt(0)
	v_add_f32_e32 v68, v68, v69
	ds_bpermute_b32 v69, v81, v68
	s_waitcnt lgkmcnt(0)
	v_add_f32_e32 v68, v68, v69
	ds_bpermute_b32 v69, v82, v68
	s_waitcnt lgkmcnt(0)
	v_add_f32_e32 v68, v68, v69
	ds_bpermute_b32 v69, v83, v68
	s_waitcnt lgkmcnt(0)
	v_add_f32_e32 v68, v68, v69
	ds_bpermute_b32 v69, v84, v68
	s_waitcnt lgkmcnt(0)
	v_add_f32_e32 v68, v68, v69
	ds_bpermute_b32 v69, v85, v68
	s_waitcnt lgkmcnt(0)
	v_add_f32_e32 v68, v68, v69
	v_fmamk_f32 v69, v68, 0x3a800000, v86
	v_mul_f32_e32 v68, 0x4b800000, v69
	v_cmp_gt_f32_e32 vcc, 0x800000, v69
	s_nop 1
	v_cndmask_b32_e32 v68, v69, v68, vcc
	v_rsq_f32_e32 v68, v68
	s_nop 0
	v_mul_f32_e32 v70, 0x45800000, v68
	v_cndmask_b32_e32 v68, v68, v70, vcc
	v_add_u32_e32 v160, 0x6800, v92
	v_mov_b32_e32 v161, 0
	v_mul_f32_e32 v69, v69, v68
	v_lshl_add_u64 v[162:163], v[160:161], 2, s[6:7]
	s_mov_b64 exec, 1
	global_store_dword v[162:163], v69, off
	s_mov_b64 exec, -1
	v_lshlrev_b64 v[162:163], 11, v[160:161]
	v_lshl_add_u64 v[162:163], v[90:91], 0, v[162:163]
	v_mul_f32_e32 v112, v112, v68
	v_mul_f32_e32 v113, v113, v68
	v_mul_f32_e32 v114, v114, v68
	v_mul_f32_e32 v115, v115, v68
	v_cvt_pk_bf16_f32 v112, v112, v113
	v_cvt_pk_bf16_f32 v113, v114, v115
	global_store_dwordx2 v[162:163], v[112:113], off
	v_mul_f32_e32 v116, v116, v68
	v_mul_f32_e32 v117, v117, v68
	v_mul_f32_e32 v118, v118, v68
	v_mul_f32_e32 v119, v119, v68
	v_cvt_pk_bf16_f32 v116, v116, v117
	v_cvt_pk_bf16_f32 v117, v118, v119
	global_store_dwordx2 v[162:163], v[116:117], off offset:512
	v_mul_f32_e32 v120, v120, v68
	v_mul_f32_e32 v121, v121, v68
	v_mul_f32_e32 v122, v122, v68
	v_mul_f32_e32 v123, v123, v68
	v_cvt_pk_bf16_f32 v120, v120, v121
	v_cvt_pk_bf16_f32 v121, v122, v123
	global_store_dwordx2 v[162:163], v[120:121], off offset:1024
	v_mul_f32_e32 v124, v124, v68
	v_mul_f32_e32 v125, v125, v68
	v_mul_f32_e32 v126, v126, v68
	v_mul_f32_e32 v127, v127, v68
	v_cvt_pk_bf16_f32 v124, v124, v125
	v_cvt_pk_bf16_f32 v125, v126, v127
	global_store_dwordx2 v[162:163], v[124:125], off offset:1536
	v_mul_f32_e32 v64, v129, v129
	v_mul_f32_e32 v65, v133, v133
	v_mul_f32_e32 v66, v137, v137
	v_mul_f32_e32 v67, v141, v141
	v_fmac_f32_e32 v64, v128, v128
	v_fmac_f32_e32 v65, v132, v132
	v_fmac_f32_e32 v66, v136, v136
	v_fmac_f32_e32 v67, v140, v140
	v_fmac_f32_e32 v64, v130, v130
	v_fmac_f32_e32 v65, v134, v134
	v_fmac_f32_e32 v66, v138, v138
	v_fmac_f32_e32 v67, v142, v142
	v_fmac_f32_e32 v64, v131, v131
	v_fmac_f32_e32 v65, v135, v135
	v_fmac_f32_e32 v66, v139, v139
	v_fmac_f32_e32 v67, v143, v143
	v_add_f32_e32 v68, v64, v65
	v_add_f32_e32 v68, v68, v66
	v_add_f32_e32 v68, v68, v67
	ds_bpermute_b32 v69, v80, v68
	s_waitcnt lgkmcnt(0)
; __device__ __forceinline__ unsigned cvt_pk_bf16(float lo, float hi) { unsigned r; asm volatile("v_cvt_pk_bf16_f32 %0, %1, %2" : "=v"(r) : "v"(lo), "v"(hi)); return r; }
; __device__ __forceinline__ void rows_prenorm(const float* __restrict__ x, bf16_t* __restrict__ XN, float* __restrict__ RN, int bi, int nb, int nrows) {
;     ...
;         for (int u = 0; u < 2; ++u) { const float* xp = x + (size_t)(row + u * nw) * DM + 4 * lane;
; #pragma unroll
;             for (int c = 0; c < 4; ++c) v[u][c] = *(const f32x4*)(xp + 256 * c); }
; #pragma unroll
;         for (int u = 0; u < 2; ++u) {
; #pragma unroll
;             for (int c = 0; c < 4; ++c) ss[u] += sq4(v[u][c]);
;             ss[u] = wave_sum(ss[u]); const float ms = ss[u] * (1.0f / DM) + EPS, ri = rsqrtf(ms);
;             if (lane == 0) RN[row + u * nw] = ms * ri;
;             bf16_t* op = XN + (size_t)(row + u * nw) * DM + 4 * lane;
; #pragma unroll
;             for (int c = 0; c < 4; ++c) { u32x2 w; w.x = cvt_pk_bf16(v[u][c][0] * ri, v[u][c][1] * ri); w.y = cvt_pk_bf16(v[u][c][2] * ri, v[u][c][3] * ri); *(u32x2*)(op + 256 * c) = w; } }
	v_add_f32_e32 v68, v68, v69
	ds_bpermute_b32 v69, v81, v68
	s_waitcnt lgkmcnt(0)
	v_add_f32_e32 v68, v68, v69
	ds_bpermute_b32 v69, v82, v68
	s_waitcnt lgkmcnt(0)
	v_add_f32_e32 v68, v68, v69
	ds_bpermute_b32 v69, v83, v68
	s_waitcnt lgkmcnt(0)
	v_add_f32_e32 v68, v68, v69
	ds_bpermute_b32 v69, v84, v68
	s_waitcnt lgkmcnt(0)
	v_add_f32_e32 v68, v68, v69
	ds_bpermute_b32 v69, v85, v68
	s_waitcnt lgkmcnt(0)
	v_add_f32_e32 v68, v68, v69
	v_fmamk_f32 v69, v68, 0x3a800000, v86
	v_mul_f32_e32 v68, 0x4b800000, v69
	v_cmp_gt_f32_e32 vcc, 0x800000, v69
	s_nop 1
	v_cndmask_b32_e32 v68, v69, v68, vcc
	v_rsq_f32_e32 v68, v68
	s_nop 0
	v_mul_f32_e32 v70, 0x45800000, v68
	v_cndmask_b32_e32 v68, v68, v70, vcc
	v_add_u32_e32 v160, 0x7000, v92
	v_mov_b32_e32 v161, 0
	v_mul_f32_e32 v69, v69, v68
	v_lshl_add_u64 v[162:163], v[160:161], 2, s[6:7]
	s_mov_b64 exec, 1
	global_store_dword v[162:163], v69, off
	s_mov_b64 exec, -1
	v_lshlrev_b64 v[162:163], 11, v[160:161]
	v_lshl_add_u64 v[162:163], v[90:91], 0, v[162:163]
	v_mul_f32_e32 v128, v128, v68
	v_mul_f32_e32 v129, v129, v68
	v_mul_f32_e32 v130, v130, v68
	v_mul_f32_e32 v131, v131, v68
	v_cvt_pk_bf16_f32 v128, v128, v129
	v_cvt_pk_bf16_f32 v129, v130, v131
	global_store_dwordx2 v[162:163], v[128:129], off
	v_mul_f32_e32 v132, v132, v68
	v_mul_f32_e32 v133, v133, v68
	v_mul_f32_e32 v134, v134, v68
	v_mul_f32_e32 v135, v135, v68
	v_cvt_pk_bf16_f32 v132, v132, v133
	v_cvt_pk_bf16_f32 v133, v134, v135
	global_store_dwordx2 v[162:163], v[132:133], off offset:512
	v_mul_f32_e32 v136, v136, v68
	v_mul_f32_e32 v137, v137, v68
	v_mul_f32_e32 v138, v138, v68
	v_mul_f32_e32 v139, v139, v68
	v_cvt_pk_bf16_f32 v136, v136, v137
	v_cvt_pk_bf16_f32 v137, v138, v139
	global_store_dwordx2 v[162:163], v[136:137], off offset:1024
	v_mul_f32_e32 v140, v140, v68
	v_mul_f32_e32 v141, v141, v68
	v_mul_f32_e32 v142, v142, v68
	v_mul_f32_e32 v143, v143, v68
	v_cvt_pk_bf16_f32 v140, v140, v141
	v_cvt_pk_bf16_f32 v141, v142, v143
	global_store_dwordx2 v[162:163], v[140:141], off offset:1536
	v_mul_f32_e32 v64, v145, v145
	v_mul_f32_e32 v65, v149, v149
	v_mul_f32_e32 v66, v153, v153
	v_mul_f32_e32 v67, v157, v157
	v_fmac_f32_e32 v64, v144, v144
	v_fmac_f32_e32 v65, v148, v148
	v_fmac_f32_e32 v66, v152, v152
	v_fmac_f32_e32 v67, v156, v156
	v_fmac_f32_e32 v64, v146, v146
	v_fmac_f32_e32 v65, v150, v150
	v_fmac_f32_e32 v66, v154, v154
	v_fmac_f32_e32 v67, v158, v158
	v_fmac_f32_e32 v64, v147, v147
	v_fmac_f32_e32 v65, v151, v151
	v_fmac_f32_e32 v66, v155, v155
	v_fmac_f32_e32 v67, v159, v159
	v_add_f32_e32 v68, v64, v65
	v_add_f32_e32 v68, v68, v66
	v_add_f32_e32 v68, v68, v67
	ds_bpermute_b32 v69, v80, v68
	s_waitcnt lgkmcnt(0)
	v_add_f32_e32 v68, v68, v69
	ds_bpermute_b32 v69, v81, v68
	s_waitcnt lgkmcnt(0)
	v_add_f32_e32 v68, v68, v69
	ds_bpermute_b32 v69, v82, v68
	s_waitcnt lgkmcnt(0)
	v_add_f32_e32 v68, v68, v69
	ds_bpermute_b32 v69, v83, v68
	s_waitcnt lgkmcnt(0)
	v_add_f32_e32 v68, v68, v69
	ds_bpermute_b32 v69, v84, v68
	s_waitcnt lgkmcnt(0)
	v_add_f32_e32 v68, v68, v69
	ds_bpermute_b32 v69, v85, v68
	s_waitcnt lgkmcnt(0)
	v_add_f32_e32 v68, v68, v69
	v_fmamk_f32 v69, v68, 0x3a800000, v86
	v_mul_f32_e32 v68, 0x4b800000, v69
	v_cmp_gt_f32_e32 vcc, 0x800000, v69
	s_nop 1
	v_cndmask_b32_e32 v68, v69, v68, vcc
	v_rsq_f32_e32 v68, v68
	s_nop 0
	v_mul_f32_e32 v70, 0x45800000, v68
	v_cndmask_b32_e32 v68, v68, v70, vcc
	v_add_u32_e32 v160, 0x7800, v92
	v_mov_b32_e32 v161, 0
	v_mul_f32_e32 v69, v69, v68
	v_lshl_add_u64 v[162:163], v[160:161], 2, s[6:7]
	s_mov_b64 exec, 1
	global_store_dword v[162:163], v69, off
	s_mov_b64 exec, -1
	v_lshlrev_b64 v[162:163], 11, v[160:161]
	v_lshl_add_u64 v[162:163], v[90:91], 0, v[162:163]
	v_mul_f32_e32 v144, v144, v68
	v_mul_f32_e32 v145, v145, v68
	v_mul_f32_e32 v146, v146, v68
	v_mul_f32_e32 v147, v147, v68
	v_cvt_pk_bf16_f32 v144, v144, v145
	v_cvt_pk_bf16_f32 v145, v146, v147
	global_store_dwordx2 v[162:163], v[144:145], off
	v_mul_f32_e32 v148, v148, v68
	v_mul_f32_e32 v149, v149, v68
	v_mul_f32_e32 v150, v150, v68
	v_mul_f32_e32 v151, v151, v68
	v_cvt_pk_bf16_f32 v148, v148, v149
	v_cvt_pk_bf16_f32 v149, v150, v151
	global_store_dwordx2 v[162:163], v[148:149], off offset:512
	v_mul_f32_e32 v152, v152, v68
	v_mul_f32_e32 v153, v153, v68
	v_mul_f32_e32 v154, v154, v68
	v_mul_f32_e32 v155, v155, v68
	v_cvt_pk_bf16_f32 v152, v152, v153
	v_cvt_pk_bf16_f32 v153, v154, v155
	global_store_dwordx2 v[162:163], v[152:153], off offset:1024
	v_mul_f32_e32 v156, v156, v68
	v_mul_f32_e32 v157, v157, v68
	v_mul_f32_e32 v158, v158, v68
	v_mul_f32_e32 v159, v159, v68
	v_cvt_pk_bf16_f32 v156, v156, v157
	v_cvt_pk_bf16_f32 v157, v158, v159
	global_store_dwordx2 v[162:163], v[156:157], off offset:1536
	v_lshlrev_b32_e32 v152, 3, v165
